# loop-edge edit: attention row-max block takes one merged wave-uniform test to the PV section (skips alpha exp / second ballot in steady state)
# speedup vs baseline: 1.0074x; 1.0055x over previous
; DEV float shfl_xor_l(float v, int m, int lane) { return __int_as_float(__builtin_amdgcn_ds_bpermute((lane ^ m) << 2, __float_as_int(v))); }
; DEV float ex2(float x) { return __builtin_amdgcn_exp2f(x); }
; DEV void attn_item(const Params& p, int layer, int h, int qb, float lam, bf16_t* lds) {
;     ...
;     float al[2];
; #pragma unroll
;     for (int i = 0; i < 2; i++) {
;       float mx = -1e30f;
; #pragma unroll
;       for (int j = 0; j < 8; j++)
; #pragma unroll
;         for (int r = 0; r < 4; r++) mx = fmaxf(mx, s[i][j][r]);
;       mx = fmaxf(mx, shfl_xor_l(mx, 16, lane));
;       mx = fmaxf(mx, shfl_xor_l(mx, 32, lane));
;       const float mold = i == 0 ? mrun0 : mrun1;
;       const float mnew = (mx > mold + 8.f) ? mx : mold;
;       al[i] = ex2(mold - mnew);
;       float ps = 0.f;
; #pragma unroll
;       for (int j = 0; j < 8; j++)
; #pragma unroll
;         for (int r = 0; r < 4; r++) { const float pv = ex2(s[i][j][r] - mnew); s[i][j][r] = pv; ps += pv; }
;       if (i == 0) { mrun0 = mnew; lrun0 = lrun0 * al[0] + ps; } else { mrun1 = mnew; lrun1 = lrun1 * al[1] + ps; }
;     }
;     if (__builtin_amdgcn_ballot_w64(al[0] != 1.f || al[1] != 1.f) != 0ull) {
.LBB0_710:
	v_max3_f32 v0, v176, s68, v177
	v_max3_f32 v0, v0, v178, v179
	v_max3_f32 v2, v168, s68, v169
	v_max3_f32 v0, v0, v172, v173
	v_max3_f32 v2, v2, v170, v171
	v_max3_f32 v0, v0, v174, v175
	v_max3_f32 v2, v2, v164, v165
	v_max3_f32 v0, v0, v160, v161
	v_max3_f32 v2, v2, v166, v167
	v_max3_f32 v0, v0, v162, v163
	v_max3_f32 v2, v2, v152, v153
	v_max3_f32 v0, v0, v156, v157
	v_max3_f32 v2, v2, v154, v155
	v_max3_f32 v0, v0, v158, v159
	v_max3_f32 v2, v2, v148, v149
	v_max3_f32 v0, v0, v144, v145
	v_max3_f32 v2, v2, v150, v151
	v_max3_f32 v0, v0, v146, v147
	v_max3_f32 v2, v2, v136, v137
	v_max3_f32 v0, v0, v140, v141
	v_max3_f32 v2, v2, v138, v139
	v_max3_f32 v0, v0, v142, v143
	v_max3_f32 v2, v2, v132, v133
	v_max3_f32 v0, v0, v128, v129
	v_max3_f32 v2, v2, v134, v135
	v_max3_f32 v0, v0, v130, v131
	v_max3_f32 v2, v2, v120, v121
	v_max3_f32 v0, v0, v124, v125
	v_max3_f32 v2, v2, v122, v123
	v_max3_f32 v0, v0, v126, v127
	v_max3_f32 v2, v2, v116, v117
	v_max3_f32 v194, v2, v118, v119
	v_mov_b32_e32 v3, v0
	v_mov_b32_e32 v195, v0
	v_mov_b32_e32 v196, v194
	v_mov_b32_e32 v197, v194
	s_nop 1
	v_permlane16_swap_b32_e32 v3, v195
	v_permlane16_swap_b32_e32 v196, v197
	v_max_f32_e32 v0, v3, v195
	v_max_f32_e32 v194, v196, v197
	v_mov_b32_e32 v3, v0
	v_mov_b32_e32 v195, v0
	v_mov_b32_e32 v196, v194
	v_mov_b32_e32 v197, v194
	s_nop 1
	v_permlane32_swap_b32_e32 v3, v195
	v_permlane32_swap_b32_e32 v196, v197
	v_max_f32_e32 v0, v3, v195
	v_max_f32_e32 v196, v196, v197
	v_sub_f32_e32 v2, v192, v212
	v_sub_f32_e32 v3, v193, v206
	s_mov_b32 s0, 0x41000000
	v_pk_add_f32 v[194:195], v[2:3], s[0:1] op_sel_hi:[1,0]
	v_cmp_gt_f32_e32 vcc, v0, v195
	s_nop 1
	v_cndmask_b32_e32 v249, v3, v0, vcc
	v_cmp_gt_f32_e32 vcc, v196, v194
	s_nop 1
	v_cndmask_b32_e32 v248, v2, v196, vcc
	v_or3_b32 v194, v2, v3, v249
	v_or_b32_e32 v194, v194, v248
	v_cmp_ne_u32_e32 vcc, 0, v194
	s_cbranch_vccnz .Lattc_slow
	v_mov_b32_e32 v2, 1.0
	v_mov_b32_e32 v3, 1.0
	s_branch .LBB0_707
.Lattc_slow:
	v_pk_add_f32 v[2:3], v[2:3], v[248:249] neg_lo:[0,1] neg_hi:[0,1]
	v_add_f32_e32 v193, v249, v206
	v_add_f32_e32 v192, v248, v212
	v_exp_f32_e32 v3, v3
	v_exp_f32_e32 v2, v2
	v_cmp_neq_f32_e32 vcc, 0, v249
	v_cmp_neq_f32_e64 s[0:1], 0, v248
	s_or_b64 vcc, s[0:1], vcc
	s_cbranch_vccz .Lattc_nofix
	v_sub_f32_e32 v176, v176, v249
	v_sub_f32_e32 v177, v177, v249
	v_sub_f32_e32 v178, v178, v249
	v_sub_f32_e32 v179, v179, v249
	v_sub_f32_e32 v168, v168, v248
	v_sub_f32_e32 v169, v169, v248
	v_sub_f32_e32 v170, v170, v248
	v_sub_f32_e32 v171, v171, v248
	v_sub_f32_e32 v172, v172, v249
	v_sub_f32_e32 v173, v173, v249
	v_sub_f32_e32 v174, v174, v249
	v_sub_f32_e32 v175, v175, v249
	v_sub_f32_e32 v164, v164, v248
	v_sub_f32_e32 v165, v165, v248
	v_sub_f32_e32 v166, v166, v248
	v_sub_f32_e32 v167, v167, v248
	v_sub_f32_e32 v160, v160, v249
	v_sub_f32_e32 v161, v161, v249
	v_sub_f32_e32 v162, v162, v249
	v_sub_f32_e32 v163, v163, v249
	v_sub_f32_e32 v152, v152, v248
	v_sub_f32_e32 v153, v153, v248
	v_sub_f32_e32 v154, v154, v248
	v_sub_f32_e32 v155, v155, v248
	v_sub_f32_e32 v156, v156, v249
	v_sub_f32_e32 v157, v157, v249
	v_sub_f32_e32 v158, v158, v249
	v_sub_f32_e32 v159, v159, v249
	v_sub_f32_e32 v148, v148, v248
	v_sub_f32_e32 v149, v149, v248
	v_sub_f32_e32 v150, v150, v248
	v_sub_f32_e32 v151, v151, v248
	v_sub_f32_e32 v144, v144, v249
	v_sub_f32_e32 v145, v145, v249
	v_sub_f32_e32 v146, v146, v249
	v_sub_f32_e32 v147, v147, v249
	v_sub_f32_e32 v136, v136, v248
	v_sub_f32_e32 v137, v137, v248
	v_sub_f32_e32 v138, v138, v248
	v_sub_f32_e32 v139, v139, v248
	v_sub_f32_e32 v140, v140, v249
	v_sub_f32_e32 v141, v141, v249
	v_sub_f32_e32 v142, v142, v249
	v_sub_f32_e32 v143, v143, v249
	v_sub_f32_e32 v132, v132, v248
	v_sub_f32_e32 v133, v133, v248
	v_sub_f32_e32 v134, v134, v248
	v_sub_f32_e32 v135, v135, v248
	v_sub_f32_e32 v128, v128, v249
	v_sub_f32_e32 v129, v129, v249
	v_sub_f32_e32 v130, v130, v249
	v_sub_f32_e32 v131, v131, v249
	v_sub_f32_e32 v120, v120, v248
	v_sub_f32_e32 v121, v121, v248
	v_sub_f32_e32 v122, v122, v248
	v_sub_f32_e32 v123, v123, v248
	v_sub_f32_e32 v124, v124, v249
	v_sub_f32_e32 v125, v125, v249
	v_sub_f32_e32 v126, v126, v249
	v_sub_f32_e32 v127, v127, v249
	v_sub_f32_e32 v116, v116, v248
	v_sub_f32_e32 v117, v117, v248
	v_sub_f32_e32 v118, v118, v248
	v_sub_f32_e32 v119, v119, v248
